# DA latent: the 8 cache tiles folded into the pipelined LDS ring loop (one 71-iteration loop, K source switches arrays at tile 8), removes old cache loop and mid-unit refill
# speedup vs baseline: 1.0013x; 1.0013x over previous
.LBB0_705:
	s_lshl_b32 s13, s9, 7
	s_add_u32 s16, s11, s13
	v_mov_b32_e32 v0, v205
	v_mov_b32_e32 v4, v206
	s_addc_u32 s17, s12, 0
	v_mov_b64_e32 v[2:3], s[16:17]
	v_mad_i64_i32 v[2:3], s[16:17], v0, s76, v[2:3]
	v_lshlrev_b32_e32 v4, 3, v4
	v_readlane_b32 s13, v252, 27
	v_ashrrev_i32_e32 v5, 31, v4
	s_add_i32 s16, s9, s13
	s_mov_b32 s17, s56
	v_lshl_add_u64 v[2:3], v[4:5], 1, v[2:3]
	s_lshl_b64 s[24:25], s[16:17], 12
	global_load_dwordx4 v[108:111], v[2:3], off
	global_load_dwordx4 v[104:107], v[2:3], off offset:32
	global_load_dwordx4 v[100:103], v[2:3], off offset:64
	global_load_dwordx4 v[96:99], v[2:3], off offset:96
	v_lshl_add_u64 v[2:3], v[152:153], 0, s[24:25]
	global_load_dwordx4 v[124:127], v[2:3], off
	global_load_dwordx4 v[120:123], v[2:3], off offset:1024
	global_load_dwordx4 v[116:119], v[2:3], off offset:2048
	global_load_dwordx4 v[112:115], v[2:3], off offset:3072
	v_mov_b32_e32 v14, v1
	v_mov_b32_e32 v15, v1
	v_mov_b32_e32 v0, v1
	v_mov_b32_e32 v2, v1
	v_mov_b32_e32 v3, v1
	v_mov_b32_e32 v4, v1
	v_mov_b32_e32 v5, v1
	v_mov_b32_e32 v6, v1
	v_mov_b32_e32 v7, v1
	v_mov_b32_e32 v8, v1
	v_mov_b32_e32 v9, v1
	v_mov_b32_e32 v10, v1
	v_mov_b32_e32 v11, v1
	v_mov_b32_e32 v12, v1
	v_mov_b32_e32 v13, v1
	v_mov_b64_e32 v[30:31], v[14:15]
	v_mov_b64_e32 v[46:47], v[14:15]
	v_mov_b64_e32 v[62:63], v[14:15]
	v_mov_b64_e32 v[78:79], v[14:15]
	s_mov_b32 s13, 7
	v_mov_b32_e32 v209, 0
	v_mov_b32_e32 v208, 0xf149f2ca
	s_mov_b64 s[26:27], s[14:15]
	s_mov_b64 s[28:29], s[6:7]
	v_mov_b64_e32 v[28:29], v[12:13]
	v_mov_b64_e32 v[26:27], v[10:11]
	v_mov_b64_e32 v[24:25], v[8:9]
	v_mov_b64_e32 v[22:23], v[6:7]
	v_mov_b64_e32 v[20:21], v[4:5]
	v_mov_b64_e32 v[18:19], v[2:3]
	v_mov_b64_e32 v[16:17], v[0:1]
	v_mov_b64_e32 v[44:45], v[12:13]
	v_mov_b64_e32 v[42:43], v[10:11]
	v_mov_b64_e32 v[40:41], v[8:9]
	v_mov_b64_e32 v[38:39], v[6:7]
	v_mov_b64_e32 v[36:37], v[4:5]
	v_mov_b64_e32 v[34:35], v[2:3]
	v_mov_b64_e32 v[32:33], v[0:1]
	v_mov_b64_e32 v[60:61], v[12:13]
	v_mov_b64_e32 v[58:59], v[10:11]
	v_mov_b64_e32 v[56:57], v[8:9]
	v_mov_b64_e32 v[54:55], v[6:7]
	v_mov_b64_e32 v[52:53], v[4:5]
	v_mov_b64_e32 v[50:51], v[2:3]
	v_mov_b64_e32 v[48:49], v[0:1]
	v_mov_b64_e32 v[76:77], v[12:13]
	v_mov_b64_e32 v[74:75], v[10:11]
	v_mov_b64_e32 v[72:73], v[8:9]
	v_mov_b64_e32 v[70:71], v[6:7]
	v_mov_b64_e32 v[68:69], v[4:5]
	v_mov_b64_e32 v[66:67], v[2:3]
	v_mov_b64_e32 v[64:65], v[0:1]
	s_waitcnt vmcnt(0)
	v_mfma_f32_32x32x16_bf16 v[80:95], v[124:127], v[108:111], 0
	v_mfma_f32_32x32x16_bf16 v[80:95], v[120:123], v[104:107], v[80:95]
	v_mfma_f32_32x32x16_bf16 v[80:95], v[116:119], v[100:103], v[80:95]
	v_mfma_f32_32x32x16_bf16 v[80:95], v[112:115], v[96:99], v[80:95]
	v_lshl_add_u64 v[14:15], v[152:153], 0, s[24:25]
	v_lshl_add_u64 v[250:251], v[154:155], 0, s[24:25]
	s_mov_b64 s[28:29], 0x10000
	s_lshr_b32 s25, s52, 6
	s_and_b32 s24, s25, 3
	s_lshl_b32 s24, s24, 11
	v_lshl_add_u64 v[14:15], s[28:29], 0, v[14:15]
	global_load_dwordx4 v[112:115], v[14:15], off
	global_load_dwordx4 v[10:13], v[14:15], off offset:1024
	global_load_dwordx4 v[6:9], v[14:15], off offset:2048
	global_load_dwordx4 v[2:5], v[14:15], off offset:3072
	s_cmp_lt_u32 s25, 4
	s_cbranch_scc0 .Lmy_pp_vsrc
	s_add_u32 s28, s24, 0x10000
	s_mov_b32 s29, 0
	v_lshl_add_u64 v[242:243], s[28:29], 0, v[14:15]
	s_mov_b32 s28, s24
	v_mov_b32_e32 v244, 0x10000
	s_nop 0
	v_lshl_add_u64 v[250:251], s[28:29], 0, v[250:251]
	s_branch .Lmy_pp_srcdone
.Lmy_pp_vsrc:
	s_add_u32 s28, s24, 0xe500000
	s_mov_b32 s29, 0
	v_lshl_add_u64 v[242:243], s[6:7], 0, v[150:151]
	v_mov_b32_e32 v244, 0x2000
	s_nop 0
	v_lshl_add_u64 v[242:243], s[28:29], 0, v[242:243]
.Lmy_pp_srcdone:
	v_mov_b32_e32 v245, 0
	v_add_u32_e32 v246, 0x10000, v150
	s_lshr_b32 s28, s25, 2
	s_lshl_b32 s28, s28, 12
	s_lshl_b32 s24, s25, 11
	s_add_i32 s24, s24, 0x10000
	v_add_u32_e32 v247, s28, v246
	s_mov_b32 m0, s24
	s_nop 0
	global_load_lds_dwordx4 v[242:243], off
	global_load_lds_dwordx4 v[242:243], off offset:1024
	v_lshl_add_u64 v[242:243], v[244:245], 0, v[242:243]
	s_add_i32 m0, s24, 0x4000
	s_nop 0
	global_load_lds_dwordx4 v[242:243], off
	global_load_lds_dwordx4 v[242:243], off offset:1024
	v_lshl_add_u64 v[242:243], v[244:245], 0, v[242:243]
	s_add_i32 m0, s24, 0x8000
	s_nop 0
	global_load_lds_dwordx4 v[242:243], off
	global_load_lds_dwordx4 v[242:243], off offset:1024
	v_lshl_add_u64 v[242:243], v[244:245], 0, v[242:243]
	s_add_i32 s24, s24, 0xc000
	s_lshr_b32 s29, s25, 2
	s_mov_b32 s25, 0
	s_mov_b32 s13, 71
	s_cmp_eq_u32 s29, 0
	s_cbranch_scc1 .Lmy_pp_noprio
	s_setprio 1

.Lmy_pp_nors_a:
	v_sub_f32_e32 v14, v80, v208
	v_exp_f32_e32 v14, v14
	v_mfma_f32_32x32x16_bf16 v[218:233], v[112:115], v[108:111], 0
	v_sub_f32_e32 v80, v81, v208
	v_exp_f32_e32 v80, v80
	v_sub_f32_e32 v81, v82, v208
	v_exp_f32_e32 v81, v81
	v_sub_f32_e32 v82, v83, v208
	v_mfma_f32_32x32x16_bf16 v[218:233], v[10:13], v[104:107], v[218:233]
	v_exp_f32_e32 v82, v82
	v_sub_f32_e32 v83, v84, v208
	v_sub_f32_e32 v84, v85, v208
	v_sub_f32_e32 v85, v86, v208
	v_sub_f32_e32 v86, v87, v208
	v_add_f32_e32 v15, 0, v14
	global_load_lds_dwordx4 v[242:243], off
	global_load_lds_dwordx4 v[242:243], off offset:1024
	v_mfma_f32_32x32x16_bf16 v[218:233], v[6:9], v[100:103], v[218:233]
	v_exp_f32_e32 v83, v83
	v_exp_f32_e32 v84, v84
	v_exp_f32_e32 v85, v85
	v_and_b32_e32 v244, s28, v244
	v_mfma_f32_32x32x16_bf16 v[218:233], v[2:5], v[96:99], v[218:233]
	v_exp_f32_e32 v86, v86
	v_lshl_add_u64 v[242:243], v[244:245], 0, v[242:243]
	s_or_b32 s24, s24, 0x10000
	s_cmp_eq_u32 s13, 69
	s_cbranch_scc0 .Lmy_pp_nsw_a
	s_cmp_lg_u32 s29, 0
	s_cbranch_scc1 .Lmy_pp_nsw_a
	v_mov_b32_e32 v242, v250
	v_mov_b32_e32 v243, v251
.Lmy_pp_nsw_a:
	ds_read_b128 v[112:115], v249
	ds_read_b128 v[10:13], v249 offset:1024
	ds_read_b128 v[6:9], v249 offset:2048
	ds_read_b128 v[2:5], v249 offset:3072
	s_add_i32 s25, s25, 0x4000
	s_and_b32 s25, s25, 0xc000
	v_add_f32_e32 v15, v80, v15
	v_add_f32_e32 v15, v81, v15
	v_add_f32_e32 v15, v82, v15
	v_add_f32_e32 v15, v83, v15
	v_cvt_pk_bf16_f32 v80, v14, v80
	v_cvt_pk_bf16_f32 v81, v81, v82
	v_cvt_pk_bf16_f32 v82, v83, v84
	v_cvt_pk_bf16_f32 v83, v85, v86
	v_sub_f32_e32 v87, v88, v208
	v_sub_f32_e32 v88, v89, v208
	s_waitcnt lgkmcnt(4)
	v_mfma_f32_32x32x16_bf16 v[64:79], v[144:147], v[80:83], v[64:79]
	v_sub_f32_e32 v89, v90, v208
	v_sub_f32_e32 v90, v91, v208
	v_sub_f32_e32 v91, v92, v208
	v_exp_f32_e32 v87, v87
	v_exp_f32_e32 v88, v88
	v_mfma_f32_32x32x16_bf16 v[48:63], v[136:139], v[80:83], v[48:63]
	v_sub_f32_e32 v92, v93, v208
	v_sub_f32_e32 v93, v94, v208
	v_sub_f32_e32 v94, v95, v208
	v_exp_f32_e32 v89, v89
	v_exp_f32_e32 v90, v90
	v_mfma_f32_32x32x16_bf16 v[32:47], v[132:135], v[80:83], v[32:47]
	v_exp_f32_e32 v91, v91
	v_exp_f32_e32 v92, v92
	v_exp_f32_e32 v93, v93
	v_exp_f32_e32 v94, v94
	v_mfma_f32_32x32x16_bf16 v[16:31], v[116:119], v[80:83], v[16:31]
	s_cmp_eq_u32 s29, 0
	s_cbranch_scc1 .Lmy_pp_nbm_a
	s_waitcnt vmcnt(4) lgkmcnt(0)
	s_barrier

.Lmy_pp_nors_b:
	v_sub_f32_e32 v14, v218, v208
	v_exp_f32_e32 v14, v14
	v_mfma_f32_32x32x16_bf16 v[80:95], v[112:115], v[108:111], 0
	v_sub_f32_e32 v218, v219, v208
	v_exp_f32_e32 v218, v218
	v_sub_f32_e32 v219, v220, v208
	v_exp_f32_e32 v219, v219
	v_sub_f32_e32 v220, v221, v208
	v_mfma_f32_32x32x16_bf16 v[80:95], v[10:13], v[104:107], v[80:95]
	v_exp_f32_e32 v220, v220
	v_sub_f32_e32 v221, v222, v208
	v_sub_f32_e32 v222, v223, v208
	v_sub_f32_e32 v223, v224, v208
	v_sub_f32_e32 v224, v225, v208
	v_add_f32_e32 v15, 0, v14
	global_load_lds_dwordx4 v[242:243], off
	global_load_lds_dwordx4 v[242:243], off offset:1024
	v_mfma_f32_32x32x16_bf16 v[80:95], v[6:9], v[100:103], v[80:95]
	v_exp_f32_e32 v221, v221
	v_exp_f32_e32 v222, v222
	v_exp_f32_e32 v223, v223
	v_and_b32_e32 v244, s28, v244
	v_mfma_f32_32x32x16_bf16 v[80:95], v[2:5], v[96:99], v[80:95]
	v_exp_f32_e32 v224, v224
	v_lshl_add_u64 v[242:243], v[244:245], 0, v[242:243]
	s_or_b32 s24, s24, 0x10000
	s_cmp_eq_u32 s13, 69
	s_cbranch_scc0 .Lmy_pp_nsw_b
	s_cmp_lg_u32 s29, 0
	s_cbranch_scc1 .Lmy_pp_nsw_b
	v_mov_b32_e32 v242, v250
	v_mov_b32_e32 v243, v251
.Lmy_pp_nsw_b:
	ds_read_b128 v[112:115], v249
	ds_read_b128 v[10:13], v249 offset:1024
	ds_read_b128 v[6:9], v249 offset:2048
	ds_read_b128 v[2:5], v249 offset:3072
	s_add_i32 s25, s25, 0x4000
	s_and_b32 s25, s25, 0xc000
	v_add_f32_e32 v15, v218, v15
	v_add_f32_e32 v15, v219, v15
	v_add_f32_e32 v15, v220, v15
	v_add_f32_e32 v15, v221, v15
	v_cvt_pk_bf16_f32 v218, v14, v218
	v_cvt_pk_bf16_f32 v219, v219, v220
	v_cvt_pk_bf16_f32 v220, v221, v222
	v_cvt_pk_bf16_f32 v221, v223, v224
	v_sub_f32_e32 v225, v226, v208
	v_sub_f32_e32 v226, v227, v208
	s_waitcnt lgkmcnt(4)
	v_mfma_f32_32x32x16_bf16 v[64:79], v[144:147], v[218:221], v[64:79]
	v_sub_f32_e32 v227, v228, v208
	v_sub_f32_e32 v228, v229, v208
	v_sub_f32_e32 v229, v230, v208
	v_exp_f32_e32 v225, v225
	v_exp_f32_e32 v226, v226
	v_mfma_f32_32x32x16_bf16 v[48:63], v[136:139], v[218:221], v[48:63]
	v_sub_f32_e32 v230, v231, v208
	v_sub_f32_e32 v231, v232, v208
	v_sub_f32_e32 v232, v233, v208
	v_exp_f32_e32 v227, v227
	v_exp_f32_e32 v228, v228
	v_mfma_f32_32x32x16_bf16 v[32:47], v[132:135], v[218:221], v[32:47]
	v_exp_f32_e32 v229, v229
	v_exp_f32_e32 v230, v230
	v_exp_f32_e32 v231, v231
	v_exp_f32_e32 v232, v232
	v_mfma_f32_32x32x16_bf16 v[16:31], v[116:119], v[218:221], v[16:31]
	s_cmp_eq_u32 s29, 0
	s_cbranch_scc1 .Lmy_pp_nbm_b
	s_waitcnt vmcnt(4) lgkmcnt(0)
	s_barrier

.Lmy_pp_nsw_t:
	s_add_i32 s25, s25, 0x4000
	s_and_b32 s25, s25, 0xc000
	v_add_f32_e32 v15, v80, v15
	v_add_f32_e32 v15, v81, v15
	v_add_f32_e32 v15, v82, v15
	v_add_f32_e32 v15, v83, v15
	v_cvt_pk_bf16_f32 v80, v14, v80
	v_cvt_pk_bf16_f32 v81, v81, v82
	v_cvt_pk_bf16_f32 v82, v83, v84
	v_cvt_pk_bf16_f32 v83, v85, v86
	v_sub_f32_e32 v87, v88, v208
	v_sub_f32_e32 v88, v89, v208
	s_waitcnt lgkmcnt(0)
	v_mfma_f32_32x32x16_bf16 v[64:79], v[144:147], v[80:83], v[64:79]
	v_sub_f32_e32 v89, v90, v208
	v_sub_f32_e32 v90, v91, v208
	v_sub_f32_e32 v91, v92, v208
	v_exp_f32_e32 v87, v87
	v_exp_f32_e32 v88, v88
	v_mfma_f32_32x32x16_bf16 v[48:63], v[136:139], v[80:83], v[48:63]
	v_sub_f32_e32 v92, v93, v208
	v_sub_f32_e32 v93, v94, v208
	v_sub_f32_e32 v94, v95, v208
	v_exp_f32_e32 v89, v89
	v_exp_f32_e32 v90, v90
	v_mfma_f32_32x32x16_bf16 v[32:47], v[132:135], v[80:83], v[32:47]
	v_exp_f32_e32 v91, v91
	v_exp_f32_e32 v92, v92
	v_exp_f32_e32 v93, v93
	v_exp_f32_e32 v94, v94
	v_mfma_f32_32x32x16_bf16 v[16:31], v[116:119], v[80:83], v[16:31]
	s_cmp_eq_u32 s29, 0
	s_cbranch_scc1 .Lmy_pp_nbm_t
	s_waitcnt vmcnt(4) lgkmcnt(0)
	s_barrier
